# thin GEMM (P7,P10): residual row load issued before the reduction barrier; on top of v15
# baseline (speedup 1.0000x reference)
; #define LAS __attribute__((address_space(3)))
; __device__ __forceinline__ void thin_gemm_ln(const bf16* A, const bf16* Bt, int K, const float* base, float s, const float* g, const float* b, float* outf, bf16* outb, ...
;     ...
;     {   const bf16* ap = A + (size_t)(32 * tm + r) * K + wave * kper + 8 * kq;
;         const bf16* bp = Bt + (size_t)(64 * tn + r) * K + wave * kper + 8 * kq;
;         f32x4m acc[2][4];
; #pragma unroll
;         for (int i = 0; i < 2; ++i)
; #pragma unroll
;             for (int j = 0; j < 4; ++j) acc[i][j] = (f32x4m){0.f, 0.f, 0.f, 0.f};
; #pragma unroll 1
;         for (int s0 = 0; s0 < steps; s0 += 4) {
;             bf16x8 fa[4][2], fb[4][4];
; #pragma unroll
;             for (int q = 0; q < 4; ++q) { const int st = (s0 + q < steps) ? s0 + q : steps - 1;
;                 fa[q][0] = *(const bf16x8*)(ap + 32 * st); fa[q][1] = *(const bf16x8*)(ap + (size_t)16 * K + 32 * st);
; #pragma unroll
;                 for (int j = 0; j < 4; ++j) fb[q][j] = *(const bf16x8*)(bp + (size_t)(16 * j) * K + 32 * st); }
; #pragma unroll
;             for (int q = 0; q < 4; ++q) if (s0 + q < steps) {
; #pragma unroll
;                 for (int j = 0; j < 4; ++j) { acc[0][j] = __builtin_amdgcn_mfma_f32_16x16x32_bf16(fa[q][0], fb[q][j], acc[0][j], 0, 0, 0); acc[1][j] = __builtin_amdgcn_mfma_f32_16x16x32_bf16(fa[q][1], fb[q][j], acc[1][j], 0, 0, 0); } }
;         }
; #pragma unroll
;         for (int i = 0; i < 2; ++i)
; #pragma unroll
;             for (int j = 0; j < 4; ++j)
; #pragma unroll
;                 for (int e = 0; e < 4; ++e) red[(wave * 32 + 16 * i + 4 * kq + e) * 64 + 16 * j + r] = acc[i][j][e]; }
;     __syncthreads();
;     const int row = tid >> 4, cg = tid & 15, grow = 32 * tm + row, gcol = 64 * tn + 4 * cg;
;     f32x4m v = (f32x4m){0.f, 0.f, 0.f, 0.f};
; #pragma unroll
;     for (int w = 0; w < 8; ++w) v += *(const LAS f32x4m*)(red + (w * 32 + row) * 64 + 4 * cg);
;     v = v * s + *(const f32x4m*)(base + (size_t)grow * DM + gcol) * ALPHA;
.LBB0_1537:
	v_mov_b32_e32 v70, v0
	s_add_u32 s12, s54, 0x40d90000
	s_addc_u32 s13, s55, 0
	v_readfirstlane_b32 s14, v70
	v_and_b32_e32 v14, 15, v70
	s_ashr_i32 s2, s14, 6
	v_or_b32_e32 v4, s77, v14
	v_ashrrev_i32_e32 v5, 31, v4
	s_lshl_b32 s0, s2, 7
	s_ashr_i32 s1, s0, 31
	v_or_b32_e32 v2, s78, v14
	v_lshlrev_b64 v[4:5], 11, v[4:5]
	v_lshlrev_b32_e32 v2, 11, v2
	v_mov_b32_e32 v3, 0
	s_lshl_b64 s[0:1], s[0:1], 1
	v_lshl_add_u64 v[4:5], s[54:55], 0, v[4:5]
	v_lshl_add_u64 v[8:9], s[84:85], 0, v[2:3]
	v_lshl_add_u64 v[4:5], v[4:5], 0, s[0:1]
	v_and_b32_e32 v2, 48, v70
	v_lshl_add_u64 v[12:13], v[4:5], 0, v[2:3]
	s_mov_b32 s3, 0x26c00000
	v_add_co_u32_e32 v4, vcc, s3, v12
	v_lshl_add_u64 v[8:9], v[8:9], 0, s[0:1]
	s_nop 0
	v_addc_co_u32_e32 v5, vcc, 0, v13, vcc
	s_mov_b32 s0, 0x26c08000
	v_add_co_u32_e32 v62, vcc, s0, v12
	v_lshl_add_u64 v[60:61], v[8:9], 0, v[2:3]
	s_nop 0
	v_addc_co_u32_e32 v63, vcc, 0, v13, vcc
	s_mov_b32 s0, 0x8000
	v_add_co_u32_e32 v64, vcc, s0, v60
	s_mov_b32 s0, 0x10000
	s_nop 0
	v_addc_co_u32_e32 v65, vcc, 0, v61, vcc
	s_barrier
	global_load_dwordx4 v[4:7], v[4:5], off
	v_add_co_u32_e32 v66, vcc, s0, v60
	global_load_dwordx4 v[8:11], v[60:61], off
	global_load_dwordx4 v[16:19], v[62:63], off
	v_addc_co_u32_e32 v67, vcc, 0, v61, vcc
	s_mov_b32 s0, 0x18000
	v_add_co_u32_e32 v68, vcc, s0, v60
	global_load_dwordx4 v[24:27], v[64:65], off
	global_load_dwordx4 v[32:35], v[66:67], off
	v_addc_co_u32_e32 v69, vcc, 0, v61, vcc
	global_load_dwordx4 v[40:43], v[68:69], off
	s_mov_b64 s[0:1], 0x26c00000
	v_lshl_add_u64 v[12:13], v[12:13], 0, s[0:1]
	global_load_dwordx4 v[44:47], v[12:13], off offset:64
	v_lshlrev_b32_e32 v2, 6, v70
	v_and_b32_e32 v2, 0xc00, v2
	v_lshl_or_b32 v2, s2, 13, v2
	v_readlane_b32 s0, v245, 61
	v_readlane_b32 s1, v245, 62
	v_cmp_eq_u32_e32 vcc, 0, v14
	global_load_dwordx4 v[88:91], v[62:63], off offset:64
	global_load_dwordx4 v[92:95], v[68:69], off offset:128
	global_load_dwordx4 v[96:99], v[60:61], off offset:64
	global_load_dwordx4 v[100:103], v[64:65], off offset:64
	global_load_dwordx4 v[104:107], v[66:67], off offset:64
	global_load_dwordx4 v[108:111], v[68:69], off offset:64
	global_load_dwordx4 v[112:115], v[12:13], off offset:128
	global_load_dwordx4 v[116:119], v[62:63], off offset:128
	global_load_dwordx4 v[120:123], v[60:61], off offset:128
	global_load_dwordx4 v[124:127], v[64:65], off offset:128
	global_load_dwordx4 v[128:131], v[66:67], off offset:128
	global_load_dwordx4 v[132:135], v[12:13], off offset:192
	global_load_dwordx4 v[136:139], v[60:61], off offset:192
	global_load_dwordx4 v[140:143], v[62:63], off offset:192
	global_load_dwordx4 v[144:147], v[64:65], off offset:192
	global_load_dwordx4 v[148:151], v[66:67], off offset:192
	global_load_dwordx4 v[152:155], v[68:69], off offset:192
	s_waitcnt vmcnt(17)
	v_mfma_f32_16x16x32_bf16 v[20:23], v[4:7], v[8:11], 0
	v_mfma_f32_16x16x32_bf16 v[8:11], v[16:19], v[8:11], 0
	v_mfma_f32_16x16x32_bf16 v[28:31], v[4:7], v[24:27], 0
	v_mfma_f32_16x16x32_bf16 v[24:27], v[16:19], v[24:27], 0
	v_mfma_f32_16x16x32_bf16 v[36:39], v[4:7], v[32:35], 0
	v_mfma_f32_16x16x32_bf16 v[32:35], v[16:19], v[32:35], 0
	v_mfma_f32_16x16x32_bf16 v[4:7], v[4:7], v[40:43], 0
	v_mfma_f32_16x16x32_bf16 v[16:19], v[16:19], v[40:43], 0
	s_waitcnt vmcnt(14)
	v_mfma_f32_16x16x32_bf16 v[20:23], v[44:47], v[96:99], v[20:23]
	v_mfma_f32_16x16x32_bf16 v[8:11], v[88:91], v[96:99], v[8:11]
	s_waitcnt vmcnt(13)
	v_mfma_f32_16x16x32_bf16 v[28:31], v[44:47], v[100:103], v[28:31]
	v_mfma_f32_16x16x32_bf16 v[24:27], v[88:91], v[100:103], v[24:27]
	s_waitcnt vmcnt(12)
	v_mfma_f32_16x16x32_bf16 v[36:39], v[44:47], v[104:107], v[36:39]
	v_mfma_f32_16x16x32_bf16 v[32:35], v[88:91], v[104:107], v[32:35]
	s_waitcnt vmcnt(11)
	v_mfma_f32_16x16x32_bf16 v[4:7], v[44:47], v[108:111], v[4:7]
	v_mfma_f32_16x16x32_bf16 v[16:19], v[88:91], v[108:111], v[16:19]
	s_waitcnt vmcnt(8)
	v_mfma_f32_16x16x32_bf16 v[20:23], v[112:115], v[120:123], v[20:23]
	v_mfma_f32_16x16x32_bf16 v[8:11], v[116:119], v[120:123], v[8:11]
	v_mfma_f32_16x16x32_bf16 v[4:7], v[112:115], v[92:95], v[4:7]
	s_waitcnt vmcnt(7)
	v_mfma_f32_16x16x32_bf16 v[28:31], v[112:115], v[124:127], v[28:31]
	v_mfma_f32_16x16x32_bf16 v[24:27], v[116:119], v[124:127], v[24:27]
	s_waitcnt vmcnt(6)
	v_mfma_f32_16x16x32_bf16 v[36:39], v[112:115], v[128:131], v[36:39]
	v_mfma_f32_16x16x32_bf16 v[32:35], v[116:119], v[128:131], v[32:35]
	v_lshlrev_b32_e32 v12, 2, v14
	v_mfma_f32_16x16x32_bf16 v[16:19], v[116:119], v[92:95], v[16:19]
	v_add3_u32 v2, 0, v12, v2
	s_waitcnt vmcnt(4)
	v_mfma_f32_16x16x32_bf16 v[20:23], v[132:135], v[136:139], v[20:23]
	v_or_b32_e32 v15, s78, v12
	v_and_b32_e32 v12, 63, v70
	s_waitcnt vmcnt(3)
	v_mfma_f32_16x16x32_bf16 v[8:11], v[140:143], v[136:139], v[8:11]
	s_waitcnt vmcnt(2)
	v_mfma_f32_16x16x32_bf16 v[28:31], v[132:135], v[144:147], v[28:31]
	s_nop 7
	ds_write2_b32 v2, v20, v28 offset1:16
	ds_write2_b32 v2, v21, v29 offset0:64 offset1:80
	ds_write2_b32 v2, v22, v30 offset0:128 offset1:144
	s_waitcnt vmcnt(1)
	v_mfma_f32_16x16x32_bf16 v[36:39], v[132:135], v[148:151], v[36:39]
	s_waitcnt vmcnt(0)
	v_mfma_f32_16x16x32_bf16 v[4:7], v[132:135], v[152:155], v[4:7]
	ds_write2_b32 v2, v23, v31 offset0:192 offset1:208
	s_nop 6
	ds_write2_b32 v2, v36, v4 offset0:32 offset1:48
	ds_write2_b32 v2, v37, v5 offset0:96 offset1:112
	v_mfma_f32_16x16x32_bf16 v[20:23], v[140:143], v[144:147], v[24:27]
	ds_write2_b32 v2, v38, v6 offset0:160 offset1:176
	ds_write2_b32 v2, v39, v7 offset0:224 offset1:240
	v_add_u32_e32 v2, 0x1000, v2
	s_nop 4
	ds_write2_b32 v2, v8, v20 offset1:16
	ds_write2_b32 v2, v9, v21 offset0:64 offset1:80
	ds_write2_b32 v2, v10, v22 offset0:128 offset1:144
	v_mfma_f32_16x16x32_bf16 v[4:7], v[140:143], v[148:151], v[32:35]
	v_ashrrev_i32_e32 v10, 4, v70
	v_add_u32_e32 v8, s77, v10
	v_ashrrev_i32_e32 v9, 31, v8
	v_mfma_f32_16x16x32_bf16 v[16:19], v[140:143], v[152:155], v[16:19]
	ds_write2_b32 v2, v11, v23 offset0:192 offset1:208
	s_nop 6
	ds_write2_b32 v2, v4, v16 offset0:32 offset1:48
	ds_write2_b32 v2, v5, v17 offset0:96 offset1:112
	ds_write2_b32 v2, v6, v18 offset0:160 offset1:176
	ds_write2_b32 v2, v7, v19 offset0:224 offset1:240
	v_lshlrev_b64 v[4:5], 12, v[8:9]
	v_lshl_add_u64 v[4:5], s[0:1], 0, v[4:5]
	v_lshlrev_b32_e32 v2, 2, v15
	v_lshl_add_u64 v[4:5], v[4:5], 0, v[2:3]
	global_load_dwordx4 v[4:7], v[4:5], off
	s_waitcnt lgkmcnt(0)
	s_barrier
; #define LAS __attribute__((address_space(3)))
; #define SDPP(x, ctrl) __builtin_bit_cast(float, __builtin_amdgcn_update_dpp(0, __builtin_bit_cast(int, (x)), (ctrl), 0xF, 0xF, false))
; __device__ __forceinline__ void thin_gemm_ln(const bf16* A, const bf16* Bt, int K, const float* base, float s, const float* g, const float* b, float* outf, bf16* outb, ...
;     ...
;     const int row = tid >> 4, cg = tid & 15, grow = 32 * tm + row, gcol = 64 * tn + 4 * cg;
;     f32x4m v = (f32x4m){0.f, 0.f, 0.f, 0.f};
; #pragma unroll
;     for (int w = 0; w < 8; ++w) v += *(const LAS f32x4m*)(red + (w * 32 + row) * 64 + 4 * cg);
;     v = v * s + *(const f32x4m*)(base + (size_t)grow * DM + gcol) * ALPHA;
;     float s1 = (v.x + v.y) + (v.z + v.w);
;     s1 += SDPP(s1, 0xB1); s1 += SDPP(s1, 0x4E); s1 += SDPP(s1, 0x141); s1 += SDPP(s1, 0x140);
;     const float mt = s1 * (1.f / 64.f); const f32x4m d = v - mt;
;     float q = (d.x * d.x + d.y * d.y) + (d.z * d.z + d.w * d.w);
;     q += SDPP(q, 0xB1); q += SDPP(q, 0x4E); q += SDPP(q, 0x141); q += SDPP(q, 0x140);
;     if (cg == 0) __hip_atomic_store(slots + (size_t)grow * 16 + tn, ((unsigned long long)__float_as_uint(q) << 32) | __float_as_uint(mt), __ATOMIC_RELAXED, __HIP_MEMORY_SCOPE_AGENT);
	v_lshlrev_b32_e32 v10, 8, v10
	v_lshlrev_b32_e32 v11, 4, v14
	v_add3_u32 v10, 0, v10, v11
	ds_read_b128 v[16:19], v10
	ds_read_b128 v[20:23], v10 offset:8192
	ds_read_b128 v[24:27], v10 offset:16384
	ds_read_b128 v[28:31], v10 offset:24576
	ds_read_b128 v[32:35], v10 offset:32768
	ds_read_b128 v[36:39], v10 offset:40960
	ds_read_b128 v[40:43], v10 offset:49152
	ds_read_b128 v[44:47], v10 offset:57344
	s_waitcnt lgkmcnt(7)
	v_pk_add_f32 v[10:11], v[18:19], 0 op_sel_hi:[1,0]
	v_pk_add_f32 v[16:17], v[16:17], 0 op_sel_hi:[1,0]
	s_waitcnt lgkmcnt(6)
	v_pk_add_f32 v[10:11], v[10:11], v[22:23]
	v_pk_add_f32 v[16:17], v[16:17], v[20:21]
	s_waitcnt lgkmcnt(5)
	v_pk_add_f32 v[10:11], v[10:11], v[26:27]
	v_pk_add_f32 v[16:17], v[16:17], v[24:25]
	s_waitcnt lgkmcnt(4)
	v_pk_add_f32 v[10:11], v[10:11], v[30:31]
	v_pk_add_f32 v[16:17], v[16:17], v[28:29]
	s_waitcnt lgkmcnt(3)
	v_pk_add_f32 v[10:11], v[10:11], v[34:35]
	v_pk_add_f32 v[16:17], v[16:17], v[32:33]
	s_waitcnt lgkmcnt(2)
	v_pk_add_f32 v[10:11], v[10:11], v[38:39]
	v_pk_add_f32 v[16:17], v[16:17], v[36:37]
	s_waitcnt lgkmcnt(1)
	v_pk_add_f32 v[10:11], v[10:11], v[42:43]
	v_pk_add_f32 v[16:17], v[16:17], v[40:41]
	s_mov_b32 s1, 0
	s_mov_b32 s0, 0x3f9837f0
	s_waitcnt lgkmcnt(0)
	v_pk_add_f32 v[10:11], v[10:11], v[46:47]
	v_pk_add_f32 v[16:17], v[16:17], v[44:45]
	s_waitcnt vmcnt(0)
	v_pk_fma_f32 v[6:7], v[6:7], s[0:1], v[10:11] op_sel_hi:[1,0,1]
	v_pk_fma_f32 v[4:5], v[4:5], s[0:1], v[16:17] op_sel_hi:[1,0,1]
	v_mov_b32_e32 v17, v7
	v_pk_mov_b32 v[10:11], v[4:5], v[6:7] op_sel:[1,0]
	v_mov_b32_e32 v16, v4
	v_pk_add_f32 v[10:11], v[10:11], v[16:17]
	s_nop 0
	v_add_f32_e32 v10, v10, v11
	s_nop 1
	v_add_f32_dpp v10, v10, v10 quad_perm:[1,0,3,2] row_mask:0xf bank_mask:0xf bound_ctrl:1
	s_nop 1
	v_add_f32_dpp v10, v10, v10 quad_perm:[2,3,0,1] row_mask:0xf bank_mask:0xf bound_ctrl:1
	s_nop 1
	v_add_f32_dpp v10, v10, v10 row_half_mirror row_mask:0xf bank_mask:0xf bound_ctrl:1
	s_nop 1
	v_add_f32_dpp v13, v10, v10 row_mirror row_mask:0xf bank_mask:0xf bound_ctrl:1
	v_fmamk_f32 v11, v13, 0xbc800000, v7
	v_fmamk_f32 v17, v13, 0xbc800000, v5
	v_fmamk_f32 v10, v13, 0xbc800000, v6
	v_fmamk_f32 v16, v13, 0xbc800000, v4
	v_mul_f32_e32 v17, v17, v17
	v_mul_f32_e32 v11, v11, v11
	v_fmac_f32_e32 v17, v16, v16
	v_fmac_f32_e32 v11, v10, v10
	v_add_f32_e32 v10, v17, v11
	s_nop 1
	v_add_f32_dpp v10, v10, v10 quad_perm:[1,0,3,2] row_mask:0xf bank_mask:0xf bound_ctrl:1
	s_nop 1
	v_add_f32_dpp v10, v10, v10 quad_perm:[2,3,0,1] row_mask:0xf bank_mask:0xf bound_ctrl:1
	s_nop 1
	v_add_f32_dpp v16, v10, v10 row_half_mirror row_mask:0xf bank_mask:0xf bound_ctrl:1
	v_lshlrev_b64 v[10:11], 7, v[8:9]
	s_nop 0
	v_mov_b32_dpp v3, v16 row_mirror row_mask:0xf bank_mask:0xf
	s_and_saveexec_b64 s[2:3], vcc
	s_cbranch_execz .LBB0_1539
	v_add_f32_e32 v19, v16, v3
	v_lshl_add_u64 v[16:17], s[12:13], 0, v[10:11]
	s_lshl_b32 s0, s76, 3
	v_mul_f32_e32 v18, 0x3c800000, v13
	v_lshl_add_u64 v[16:17], v[16:17], 0, s[0:1]
	global_store_dwordx2 v[16:17], v[18:19], off sc1

; #define LAS __attribute__((address_space(3)))
; #define SDPP(x, ctrl) __builtin_bit_cast(float, __builtin_amdgcn_update_dpp(0, __builtin_bit_cast(int, (x)), (ctrl), 0xF, 0xF, false))
; __device__ __forceinline__ void thin_gemm_ln(const bf16* A, const bf16* Bt, int K, const float* base, float s, const float* g, const float* b, float* outf, bf16* outb, ...
;     ...
; #pragma unroll
;         for (int i = 0; i < 2; ++i)
; #pragma unroll
;             for (int j = 0; j < 4; ++j)
; #pragma unroll
;                 for (int e = 0; e < 4; ++e) red[(wave * 32 + 16 * i + 4 * kq + e) * 64 + 16 * j + r] = acc[i][j][e]; }
;     __syncthreads();
;     const int row = tid >> 4, cg = tid & 15, grow = 32 * tm + row, gcol = 64 * tn + 4 * cg;
;     f32x4m v = (f32x4m){0.f, 0.f, 0.f, 0.f};
; #pragma unroll
;     for (int w = 0; w < 8; ++w) v += *(const LAS f32x4m*)(red + (w * 32 + row) * 64 + 4 * cg);
;     v = v * s + *(const f32x4m*)(base + (size_t)grow * DM + gcol) * ALPHA;
;     float s1 = (v.x + v.y) + (v.z + v.w);
;     s1 += SDPP(s1, 0xB1); s1 += SDPP(s1, 0x4E); s1 += SDPP(s1, 0x141); s1 += SDPP(s1, 0x140);
;     const float mt = s1 * (1.f / 64.f); const f32x4m d = v - mt;
;     float q = (d.x * d.x + d.y * d.y) + (d.z * d.z + d.w * d.w);
;     q += SDPP(q, 0xB1); q += SDPP(q, 0x4E); q += SDPP(q, 0x141); q += SDPP(q, 0x140);
;     if (cg == 0) __hip_atomic_store(slots + (size_t)grow * 16 + tn, ((unsigned long long)__float_as_uint(q) << 32) | __float_as_uint(mt), __ATOMIC_RELAXED, __HIP_MEMORY_SCOPE_AGENT);
.LBB0_1760:
	v_lshlrev_b32_e32 v1, 6, v0
	v_and_b32_e32 v1, 0xc00, v1
	v_lshl_or_b32 v1, s4, 13, v1
	v_lshlrev_b32_e32 v34, 2, v42
	v_add3_u32 v1, 0, v34, v1
	ds_write2_b32 v1, v2, v30 offset1:16
	ds_write2_b32 v1, v3, v31 offset0:64 offset1:80
	ds_write2_b32 v1, v4, v32 offset0:128 offset1:144
	ds_write2_b32 v1, v5, v33 offset0:192 offset1:208
	ds_write2_b32 v1, v26, v22 offset0:32 offset1:48
	ds_write2_b32 v1, v27, v23 offset0:96 offset1:112
	ds_write2_b32 v1, v28, v24 offset0:160 offset1:176
	ds_write2_b32 v1, v29, v25 offset0:224 offset1:240
	v_add_u32_e32 v1, 0x1000, v1
	ds_write2_b32 v1, v14, v18 offset1:16
	ds_write2_b32 v1, v15, v19 offset0:64 offset1:80
	ds_write2_b32 v1, v16, v20 offset0:128 offset1:144
	ds_write2_b32 v1, v17, v21 offset0:192 offset1:208
	ds_write2_b32 v1, v6, v10 offset0:32 offset1:48
	ds_write2_b32 v1, v7, v11 offset0:96 offset1:112
	ds_write2_b32 v1, v8, v12 offset0:160 offset1:176
	ds_write2_b32 v1, v9, v13 offset0:224 offset1:240
	v_ashrrev_i32_e32 v1, 4, v0
	v_add_u32_e32 v6, s77, v1
	v_ashrrev_i32_e32 v7, 31, v6
	v_or_b32_e32 v8, s78, v34
	v_lshlrev_b64 v[2:3], 12, v[6:7]
	v_lshl_add_u64 v[4:5], s[8:9], 0, v[2:3]
	v_mov_b32_e32 v3, 0
	v_lshlrev_b32_e32 v2, 2, v8
	v_lshl_add_u64 v[4:5], v[4:5], 0, v[2:3]
	global_load_dwordx4 v[12:15], v[4:5], off
	s_waitcnt lgkmcnt(0)
	s_barrier
	v_and_b32_e32 v10, 63, v0
	v_lshlrev_b32_e32 v0, 4, v42
	v_lshlrev_b32_e32 v1, 8, v1
	v_add3_u32 v0, 0, v1, v0
	ds_read_b128 v[16:19], v0
	ds_read_b128 v[20:23], v0 offset:8192
	ds_read_b128 v[24:27], v0 offset:16384
	ds_read_b128 v[28:31], v0 offset:24576
	ds_read_b128 v[32:35], v0 offset:32768
	ds_read_b128 v[36:39], v0 offset:40960
	ds_read_b128 v[44:47], v0 offset:49152
	ds_read_b128 v[48:51], v0 offset:57344
	s_waitcnt lgkmcnt(7)
	v_pk_add_f32 v[0:1], v[18:19], 0 op_sel_hi:[1,0]
	v_pk_add_f32 v[4:5], v[16:17], 0 op_sel_hi:[1,0]
	s_waitcnt lgkmcnt(6)
	v_pk_add_f32 v[0:1], v[0:1], v[22:23]
	v_pk_add_f32 v[4:5], v[4:5], v[20:21]
	s_waitcnt lgkmcnt(5)
	v_pk_add_f32 v[0:1], v[0:1], v[26:27]
	v_pk_add_f32 v[4:5], v[4:5], v[24:25]
	s_waitcnt lgkmcnt(4)
	v_pk_add_f32 v[0:1], v[0:1], v[30:31]
	v_pk_add_f32 v[4:5], v[4:5], v[28:29]
	s_waitcnt lgkmcnt(3)
	v_pk_add_f32 v[0:1], v[0:1], v[34:35]
	v_pk_add_f32 v[4:5], v[4:5], v[32:33]
	s_waitcnt lgkmcnt(2)
	v_pk_add_f32 v[0:1], v[0:1], v[38:39]
	v_pk_add_f32 v[4:5], v[4:5], v[36:37]
	s_mov_b32 s1, 0
	s_mov_b32 s0, 0x3f9837f0
	s_waitcnt lgkmcnt(1)
	v_pk_add_f32 v[0:1], v[0:1], v[46:47]
	v_pk_add_f32 v[4:5], v[4:5], v[44:45]
	s_waitcnt lgkmcnt(0)
	v_pk_add_f32 v[0:1], v[0:1], v[50:51]
	v_pk_add_f32 v[8:9], v[4:5], v[48:49]
	s_add_u32 s4, s54, 0x40da0000
	v_cmp_eq_u32_e32 vcc, 0, v42
	s_addc_u32 s5, s55, 0
	s_waitcnt vmcnt(0)
	v_pk_mul_f32 v[4:5], v[14:15], s[0:1] op_sel_hi:[1,0]
	v_pk_mul_f32 v[12:13], v[12:13], s[0:1] op_sel_hi:[1,0]
	v_pk_fma_f32 v[4:5], v[0:1], 0.5, v[4:5] op_sel_hi:[1,0,1]
	v_pk_fma_f32 v[0:1], v[8:9], 0.5, v[12:13] op_sel_hi:[1,0,1]
	v_mov_b32_e32 v13, v5
	v_pk_mov_b32 v[8:9], v[0:1], v[4:5] op_sel:[1,0]
	v_mov_b32_e32 v12, v0
	v_pk_add_f32 v[8:9], v[8:9], v[12:13]
	s_nop 0
	v_add_f32_e32 v8, v8, v9
	s_nop 1
	v_add_f32_dpp v8, v8, v8 quad_perm:[1,0,3,2] row_mask:0xf bank_mask:0xf bound_ctrl:1
	s_nop 1
	v_add_f32_dpp v8, v8, v8 quad_perm:[2,3,0,1] row_mask:0xf bank_mask:0xf bound_ctrl:1
	s_nop 1
	v_add_f32_dpp v8, v8, v8 row_half_mirror row_mask:0xf bank_mask:0xf bound_ctrl:1
	s_nop 1
	v_add_f32_dpp v11, v8, v8 row_mirror row_mask:0xf bank_mask:0xf bound_ctrl:1
	v_fmamk_f32 v9, v11, 0xbc800000, v5
	v_fmamk_f32 v13, v11, 0xbc800000, v1
	v_fmamk_f32 v8, v11, 0xbc800000, v4
	v_fmamk_f32 v12, v11, 0xbc800000, v0
	v_mul_f32_e32 v13, v13, v13
	v_mul_f32_e32 v9, v9, v9
	v_fmac_f32_e32 v13, v12, v12
	v_fmac_f32_e32 v9, v8, v8
	v_add_f32_e32 v8, v13, v9
	s_nop 1
	v_add_f32_dpp v8, v8, v8 quad_perm:[1,0,3,2] row_mask:0xf bank_mask:0xf bound_ctrl:1
	s_nop 1
	v_add_f32_dpp v8, v8, v8 quad_perm:[2,3,0,1] row_mask:0xf bank_mask:0xf bound_ctrl:1
	s_nop 1
	v_add_f32_dpp v12, v8, v8 row_half_mirror row_mask:0xf bank_mask:0xf bound_ctrl:1
	v_lshlrev_b64 v[8:9], 7, v[6:7]
	s_nop 0
	v_mov_b32_dpp v3, v12 row_mirror row_mask:0xf bank_mask:0xf
	s_and_saveexec_b64 s[2:3], vcc
	s_cbranch_execz .LBB0_1762
	v_add_f32_e32 v15, v12, v3
	v_lshl_add_u64 v[12:13], s[4:5], 0, v[8:9]
	s_lshl_b32 s0, s76, 3
	v_mul_f32_e32 v14, 0x3c800000, v11
	v_lshl_add_u64 v[12:13], v[12:13], 0, s[0:1]
	global_store_dwordx2 v[12:13], v[14:15], off sc1
